# P8 epilogue y stores marked sc1 (write-through, not retained in L2)
# baseline (speedup 1.0000x reference)
.LBB0_2144:
	s_lshl_b32 s8, s8, 8
	s_add_i32 s8, s8, s39
	v_or_b32_e32 v222, s8, v146
	v_add_u32_e32 v160, 0xffff8000, v222
	v_cmp_gt_i32_e32 vcc, s51, v222
	v_readlane_b32 s0, v242, 47
	v_lshl_or_b32 v142, s54, 8, v150
	v_cndmask_b32_e32 v144, v160, v222, vcc
	v_readlane_b32 s1, v242, 48
	v_ashrrev_i32_e32 v145, 31, v144
	v_ashrrev_i32_e32 v143, 31, v142
	v_mov_b32_e32 v154, s41
	v_mov_b32_e32 v155, s1
	v_mov_b32_e32 v156, s40
	v_mov_b32_e32 v157, s0
	v_lshlrev_b64 v[144:145], 10, v[144:145]
	s_ashr_i32 s0, s8, 11
	v_lshrrev_b32_e32 v160, 3, v160
	v_cndmask_b32_e32 v159, v154, v155, vcc
	v_cndmask_b32_e32 v158, v156, v157, vcc
	v_lshl_add_u64 v[194:195], v[144:145], 0, v[142:143]
	v_add_u32_e32 v160, 16, v160
	v_mov_b32_e32 v223, s0
	v_lshl_add_u64 v[158:159], v[194:195], 1, v[158:159]
	v_lshl_add_u64 v[144:145], v[142:143], 2, s[12:13]
	v_cndmask_b32_e32 v160, v160, v223, vcc
	global_load_dwordx2 v[196:197], v[158:159], off
	global_load_dwordx2 v[198:199], v[158:159], off offset:32
	global_load_dwordx2 v[200:201], v[158:159], off offset:256
	v_mad_i64_i32 v[160:161], s[0:1], v160, s38, v[144:145]
	global_load_dwordx2 v[202:203], v[158:159], off offset:288
	global_load_dwordx4 v[162:165], v[160:161], off
	global_load_dwordx4 v[166:169], v[160:161], off offset:64
	global_load_dwordx4 v[170:173], v[160:161], off offset:512
	global_load_dwordx4 v[174:177], v[160:161], off offset:576
	v_or_b32_e32 v158, 16, v222
	v_add_u32_e32 v178, 0xffff8010, v222
	v_cmp_gt_i32_e64 s[6:7], s51, v158
	v_readlane_b32 s56, v242, 2
	v_readlane_b32 s57, v242, 3
	v_cndmask_b32_e64 v158, v178, v158, s[6:7]
	v_ashrrev_i32_e32 v159, 31, v158
	v_lshlrev_b64 v[158:159], 10, v[158:159]
	v_cndmask_b32_e64 v161, v154, v155, s[6:7]
	v_cndmask_b32_e64 v160, v156, v157, s[6:7]
	v_lshl_add_u64 v[204:205], v[158:159], 0, v[142:143]
	v_lshl_add_u64 v[158:159], v[204:205], 1, v[160:161]
	global_load_dwordx2 v[206:207], v[158:159], off
	v_lshrrev_b32_e32 v160, 3, v178
	v_add_u32_e32 v160, 16, v160
	v_cndmask_b32_e64 v160, v160, v223, s[6:7]
	v_mad_i64_i32 v[160:161], s[0:1], v160, s38, v[144:145]
	global_load_dwordx4 v[178:181], v[160:161], off
	global_load_dwordx2 v[208:209], v[158:159], off offset:32
	global_load_dwordx4 v[182:185], v[160:161], off offset:64
	global_load_dwordx2 v[210:211], v[158:159], off offset:256
	global_load_dwordx4 v[186:189], v[160:161], off offset:512
	global_load_dwordx2 v[212:213], v[158:159], off offset:288
	global_load_dwordx4 v[190:193], v[160:161], off offset:576
	s_mov_b64 s[0:1], s[56:57]
	v_mov_b32_e32 v158, s43
	v_mov_b32_e32 v159, s1
	v_mov_b32_e32 v160, s42
	v_mov_b32_e32 v161, s0
	v_cndmask_b32_e32 v215, v158, v159, vcc
	v_cndmask_b32_e32 v214, v160, v161, vcc
	v_cndmask_b32_e64 v217, v158, v159, s[6:7]
	v_cndmask_b32_e64 v216, v160, v161, s[6:7]
	v_lshl_add_u64 v[194:195], v[194:195], 2, v[214:215]
	v_lshl_add_u64 v[204:205], v[204:205], 2, v[216:217]
	s_addk_i32 s8, 0x80
	v_readlane_b32 s58, v242, 4
	v_readlane_b32 s59, v242, 5
	s_waitcnt vmcnt(0)
	v_lshlrev_b32_e32 v214, 16, v196
	v_and_b32_e32 v215, 0xffff0000, v196
	v_lshlrev_b32_e32 v196, 16, v197
	v_and_b32_e32 v197, 0xffff0000, v197
	v_lshlrev_b32_e32 v220, 16, v202
	v_and_b32_e32 v221, 0xffff0000, v202
	v_lshlrev_b32_e32 v202, 16, v203
	v_and_b32_e32 v203, 0xffff0000, v203
	v_lshlrev_b32_e32 v216, 16, v198
	v_and_b32_e32 v217, 0xffff0000, v198
	v_lshlrev_b32_e32 v198, 16, v199
	v_and_b32_e32 v199, 0xffff0000, v199
	v_lshlrev_b32_e32 v218, 16, v200
	v_and_b32_e32 v219, 0xffff0000, v200
	v_lshlrev_b32_e32 v200, 16, v201
	v_and_b32_e32 v201, 0xffff0000, v201
	v_pk_fma_f32 v[126:127], v[126:127], v[164:165], v[196:197]
	v_pk_fma_f32 v[124:125], v[124:125], v[162:163], v[214:215]
	v_pk_fma_f32 v[110:111], v[110:111], v[176:177], v[202:203]
	v_pk_fma_f32 v[108:109], v[108:109], v[174:175], v[220:221]
	v_pk_fma_f32 v[122:123], v[122:123], v[168:169], v[198:199]
	v_pk_fma_f32 v[120:121], v[120:121], v[166:167], v[216:217]
	v_pk_fma_f32 v[118:119], v[118:119], v[172:173], v[200:201]
	v_pk_fma_f32 v[116:117], v[116:117], v[170:171], v[218:219]
	global_store_dwordx4 v[194:195], v[124:127], off sc1
	global_store_dwordx4 v[194:195], v[120:123], off offset:64 sc1
	global_store_dwordx4 v[194:195], v[116:119], off offset:512 sc1
	global_store_dwordx4 v[194:195], v[108:111], off offset:576 sc1
	s_nop 0
	v_add_u32_e32 v116, 0xffff8030, v222
	v_lshlrev_b32_e32 v108, 16, v206
	v_and_b32_e32 v109, 0xffff0000, v206
	v_lshlrev_b32_e32 v110, 16, v207
	v_and_b32_e32 v111, 0xffff0000, v207
	v_pk_fma_f32 v[110:111], v[114:115], v[180:181], v[110:111]
	v_pk_fma_f32 v[108:109], v[112:113], v[178:179], v[108:109]
	global_store_dwordx4 v[204:205], v[108:111], off sc1
	v_or_b32_e32 v112, 48, v222
	v_cmp_gt_i32_e64 s[6:7], s51, v112
	v_lshlrev_b32_e32 v108, 16, v208
	v_and_b32_e32 v109, 0xffff0000, v208
	v_lshlrev_b32_e32 v110, 16, v209
	v_and_b32_e32 v111, 0xffff0000, v209
	v_pk_fma_f32 v[106:107], v[106:107], v[184:185], v[110:111]
	v_pk_fma_f32 v[104:105], v[104:105], v[182:183], v[108:109]
	global_store_dwordx4 v[204:205], v[104:107], off offset:64 sc1
	v_cndmask_b32_e64 v112, v116, v112, s[6:7]
	v_ashrrev_i32_e32 v113, 31, v112
	v_lshlrev_b32_e32 v104, 16, v210
	v_and_b32_e32 v105, 0xffff0000, v210
	v_lshlrev_b32_e32 v106, 16, v211
	v_and_b32_e32 v107, 0xffff0000, v211
	v_pk_fma_f32 v[102:103], v[102:103], v[188:189], v[106:107]
	v_pk_fma_f32 v[100:101], v[100:101], v[186:187], v[104:105]
	global_store_dwordx4 v[204:205], v[100:103], off offset:512 sc1
	v_lshlrev_b64 v[112:113], 10, v[112:113]
	v_cndmask_b32_e64 v115, v154, v155, s[6:7]
	v_lshlrev_b32_e32 v100, 16, v212
	v_and_b32_e32 v101, 0xffff0000, v212
	v_lshlrev_b32_e32 v102, 16, v213
	v_and_b32_e32 v103, 0xffff0000, v213
	v_pk_fma_f32 v[98:99], v[98:99], v[192:193], v[102:103]
	v_pk_fma_f32 v[96:97], v[96:97], v[190:191], v[100:101]
	global_store_dwordx4 v[204:205], v[96:99], off offset:576 sc1
	v_add_u32_e32 v100, 0xffff8020, v222
	v_cndmask_b32_e64 v114, v156, v157, s[6:7]
	v_or_b32_e32 v96, 32, v222
	v_cmp_gt_i32_e32 vcc, s51, v96
	v_lshl_add_u64 v[172:173], v[112:113], 0, v[142:143]
	v_lshl_add_u64 v[124:125], v[172:173], 1, v[114:115]
	v_cndmask_b32_e32 v96, v100, v96, vcc
	v_ashrrev_i32_e32 v97, 31, v96
	v_lshlrev_b64 v[96:97], 10, v[96:97]
	v_cndmask_b32_e32 v99, v154, v155, vcc
	v_cndmask_b32_e32 v98, v156, v157, vcc
	v_lshl_add_u64 v[162:163], v[96:97], 0, v[142:143]
	v_lshl_add_u64 v[104:105], v[162:163], 1, v[98:99]
	global_load_dwordx2 v[164:165], v[104:105], off
	v_lshrrev_b32_e32 v96, 3, v100
	v_add_u32_e32 v96, 16, v96
	v_cndmask_b32_e32 v96, v96, v223, vcc
	v_mad_i64_i32 v[108:109], s[0:1], v96, s38, v[144:145]
	global_load_dwordx4 v[96:99], v[108:109], off
	global_load_dwordx2 v[166:167], v[104:105], off offset:32
	global_load_dwordx4 v[100:103], v[108:109], off offset:64
	global_load_dwordx2 v[168:169], v[104:105], off offset:256
	global_load_dwordx2 v[170:171], v[104:105], off offset:288
	s_nop 0
	global_load_dwordx4 v[104:107], v[108:109], off offset:512
	s_nop 0
	global_load_dwordx4 v[108:111], v[108:109], off offset:576
	v_lshrrev_b32_e32 v112, 3, v116
	global_load_dwordx2 v[174:175], v[124:125], off
	v_add_u32_e32 v112, 16, v112
	v_cndmask_b32_e64 v112, v112, v223, s[6:7]
	v_mad_i64_i32 v[126:127], s[0:1], v112, s38, v[144:145]
	global_load_dwordx4 v[112:115], v[126:127], off
	global_load_dwordx2 v[176:177], v[124:125], off offset:32
	global_load_dwordx4 v[116:119], v[126:127], off offset:64
	global_load_dwordx2 v[178:179], v[124:125], off offset:256
	global_load_dwordx4 v[120:123], v[126:127], off offset:512
	global_load_dwordx2 v[180:181], v[124:125], off offset:288
	s_nop 0
	global_load_dwordx4 v[124:127], v[126:127], off offset:576
	v_cndmask_b32_e32 v183, v158, v159, vcc
	v_cndmask_b32_e32 v182, v160, v161, vcc
	v_lshl_add_u64 v[162:163], v[162:163], 2, v[182:183]
	v_cndmask_b32_e64 v183, v158, v159, s[6:7]
	v_cndmask_b32_e64 v182, v160, v161, s[6:7]
	v_lshl_add_u64 v[172:173], v[172:173], 2, v[182:183]
	s_ashr_i32 s0, s8, 11
	s_waitcnt vmcnt(15)
	v_lshlrev_b32_e32 v182, 16, v164
	v_and_b32_e32 v183, 0xffff0000, v164
	v_lshlrev_b32_e32 v164, 16, v165
	v_and_b32_e32 v165, 0xffff0000, v165
	s_waitcnt vmcnt(14)
	v_pk_fma_f32 v[94:95], v[94:95], v[98:99], v[164:165]
	v_pk_fma_f32 v[92:93], v[92:93], v[96:97], v[182:183]
	global_store_dwordx4 v[162:163], v[92:95], off sc1
	s_waitcnt vmcnt(14)
	s_nop 0
	v_lshlrev_b32_e32 v92, 16, v166
	v_and_b32_e32 v93, 0xffff0000, v166
	v_lshlrev_b32_e32 v94, 16, v167
	v_and_b32_e32 v95, 0xffff0000, v167
	s_waitcnt vmcnt(13)
	v_pk_fma_f32 v[90:91], v[90:91], v[102:103], v[94:95]
	v_pk_fma_f32 v[88:89], v[88:89], v[100:101], v[92:93]
	global_store_dwordx4 v[162:163], v[88:91], off offset:64 sc1
	s_waitcnt vmcnt(13)
	s_nop 0
	v_lshlrev_b32_e32 v88, 16, v168
	v_and_b32_e32 v89, 0xffff0000, v168
	v_lshlrev_b32_e32 v90, 16, v169
	v_and_b32_e32 v91, 0xffff0000, v169
	s_waitcnt vmcnt(11)
	v_pk_fma_f32 v[86:87], v[86:87], v[106:107], v[90:91]
	v_pk_fma_f32 v[84:85], v[84:85], v[104:105], v[88:89]
	global_store_dwordx4 v[162:163], v[84:87], off offset:512 sc1
	s_nop 1
	v_lshlrev_b32_e32 v84, 16, v170
	v_and_b32_e32 v85, 0xffff0000, v170
	v_lshlrev_b32_e32 v86, 16, v171
	v_and_b32_e32 v87, 0xffff0000, v171
	s_waitcnt vmcnt(11)
	v_pk_fma_f32 v[78:79], v[78:79], v[110:111], v[86:87]
	v_pk_fma_f32 v[76:77], v[76:77], v[108:109], v[84:85]
	global_store_dwordx4 v[162:163], v[76:79], off offset:576 sc1
	s_waitcnt vmcnt(11)
	s_nop 0
	v_lshlrev_b32_e32 v76, 16, v174
	v_and_b32_e32 v77, 0xffff0000, v174
	v_lshlrev_b32_e32 v78, 16, v175
	v_and_b32_e32 v79, 0xffff0000, v175
	s_waitcnt vmcnt(10)
	v_pk_fma_f32 v[78:79], v[82:83], v[114:115], v[78:79]
	v_pk_fma_f32 v[76:77], v[80:81], v[112:113], v[76:77]
	global_store_dwordx4 v[172:173], v[76:79], off sc1
	s_waitcnt vmcnt(10)
	s_nop 0
	v_lshlrev_b32_e32 v76, 16, v176
	v_and_b32_e32 v77, 0xffff0000, v176
	v_lshlrev_b32_e32 v78, 16, v177
	v_and_b32_e32 v79, 0xffff0000, v177
	s_waitcnt vmcnt(9)
	v_pk_fma_f32 v[74:75], v[74:75], v[118:119], v[78:79]
	v_pk_fma_f32 v[72:73], v[72:73], v[116:117], v[76:77]
	global_store_dwordx4 v[172:173], v[72:75], off offset:64 sc1
	v_or_b32_e32 v118, s8, v146
	v_cmp_gt_i32_e32 vcc, s51, v118
	s_waitcnt vmcnt(9)
	v_lshlrev_b32_e32 v72, 16, v178
	v_and_b32_e32 v73, 0xffff0000, v178
	v_lshlrev_b32_e32 v74, 16, v179
	v_and_b32_e32 v75, 0xffff0000, v179
	s_waitcnt vmcnt(8)
	v_pk_fma_f32 v[70:71], v[70:71], v[122:123], v[74:75]
	v_pk_fma_f32 v[68:69], v[68:69], v[120:121], v[72:73]
	global_store_dwordx4 v[172:173], v[68:71], off offset:512 sc1
	v_or_b32_e32 v80, 16, v118
	v_add_u32_e32 v84, 0xffff8010, v118
	s_waitcnt vmcnt(8)
	v_lshlrev_b32_e32 v68, 16, v180
	v_and_b32_e32 v69, 0xffff0000, v180
	v_lshlrev_b32_e32 v70, 16, v181
	v_and_b32_e32 v71, 0xffff0000, v181
	s_waitcnt vmcnt(7)
	v_pk_fma_f32 v[66:67], v[66:67], v[126:127], v[70:71]
	v_pk_fma_f32 v[64:65], v[64:65], v[124:125], v[68:69]
	v_add_u32_e32 v68, 0xffff8000, v118
	global_store_dwordx4 v[172:173], v[64:67], off offset:576 sc1
	v_cmp_gt_i32_e64 s[6:7], s51, v80
	v_mov_b32_e32 v119, s0
	v_cndmask_b32_e32 v64, v68, v118, vcc
	v_ashrrev_i32_e32 v65, 31, v64
	v_lshlrev_b64 v[64:65], 10, v[64:65]
	v_cndmask_b32_e32 v67, v154, v155, vcc
	v_cndmask_b32_e32 v66, v156, v157, vcc
	v_lshl_add_u64 v[96:97], v[64:65], 0, v[142:143]
	v_lshl_add_u64 v[72:73], v[96:97], 1, v[66:67]
	global_load_dwordx2 v[98:99], v[72:73], off
	v_lshrrev_b32_e32 v64, 3, v68
	v_add_u32_e32 v64, 16, v64
	v_cndmask_b32_e64 v80, v84, v80, s[6:7]
	v_cndmask_b32_e32 v64, v64, v119, vcc
	v_ashrrev_i32_e32 v81, 31, v80
	v_mad_i64_i32 v[76:77], s[0:1], v64, s38, v[144:145]
	v_lshlrev_b64 v[80:81], 10, v[80:81]
	global_load_dwordx4 v[64:67], v[76:77], off
	global_load_dwordx2 v[100:101], v[72:73], off offset:32
	global_load_dwordx4 v[68:71], v[76:77], off offset:64
	global_load_dwordx2 v[102:103], v[72:73], off offset:256
	global_load_dwordx2 v[104:105], v[72:73], off offset:288
	s_nop 0
	global_load_dwordx4 v[72:75], v[76:77], off offset:512
	s_nop 0
	global_load_dwordx4 v[76:79], v[76:77], off offset:576
	v_cndmask_b32_e64 v83, v154, v155, s[6:7]
	v_cndmask_b32_e64 v82, v156, v157, s[6:7]
	v_lshl_add_u64 v[106:107], v[80:81], 0, v[142:143]
	v_lshl_add_u64 v[92:93], v[106:107], 1, v[82:83]
	global_load_dwordx2 v[108:109], v[92:93], off
	v_lshrrev_b32_e32 v80, 3, v84
	v_add_u32_e32 v80, 16, v80
	v_cndmask_b32_e64 v80, v80, v119, s[6:7]
	v_mad_i64_i32 v[94:95], s[0:1], v80, s38, v[144:145]
	global_load_dwordx4 v[80:83], v[94:95], off
	global_load_dwordx2 v[110:111], v[92:93], off offset:32
	global_load_dwordx4 v[84:87], v[94:95], off offset:64
	global_load_dwordx2 v[112:113], v[92:93], off offset:256
	global_load_dwordx4 v[88:91], v[94:95], off offset:512
	global_load_dwordx2 v[114:115], v[92:93], off offset:288
	s_nop 0
	global_load_dwordx4 v[92:95], v[94:95], off offset:576
	v_cndmask_b32_e32 v117, v158, v159, vcc
	v_cndmask_b32_e32 v116, v160, v161, vcc
	v_lshl_add_u64 v[96:97], v[96:97], 2, v[116:117]
	v_cndmask_b32_e64 v117, v158, v159, s[6:7]
	v_cndmask_b32_e64 v116, v160, v161, s[6:7]
	v_lshl_add_u64 v[106:107], v[106:107], 2, v[116:117]
	s_waitcnt vmcnt(15)
	v_lshlrev_b32_e32 v116, 16, v98
	v_and_b32_e32 v117, 0xffff0000, v98
	v_lshlrev_b32_e32 v98, 16, v99
	v_and_b32_e32 v99, 0xffff0000, v99
	s_waitcnt vmcnt(14)
	v_pk_fma_f32 v[62:63], v[62:63], v[66:67], v[98:99]
	v_pk_fma_f32 v[60:61], v[60:61], v[64:65], v[116:117]
	global_store_dwordx4 v[96:97], v[60:63], off sc1
	s_waitcnt vmcnt(14)
	s_nop 0
	v_lshlrev_b32_e32 v60, 16, v100
	v_and_b32_e32 v61, 0xffff0000, v100
	v_lshlrev_b32_e32 v62, 16, v101
	v_and_b32_e32 v63, 0xffff0000, v101
	s_waitcnt vmcnt(13)
	v_pk_fma_f32 v[58:59], v[58:59], v[70:71], v[62:63]
	v_pk_fma_f32 v[56:57], v[56:57], v[68:69], v[60:61]
	global_store_dwordx4 v[96:97], v[56:59], off offset:64 sc1
	s_waitcnt vmcnt(13)
	s_nop 0
	v_lshlrev_b32_e32 v56, 16, v102
	v_and_b32_e32 v57, 0xffff0000, v102
	v_lshlrev_b32_e32 v58, 16, v103
	v_and_b32_e32 v59, 0xffff0000, v103
	s_waitcnt vmcnt(11)
	v_pk_fma_f32 v[54:55], v[54:55], v[74:75], v[58:59]
	v_pk_fma_f32 v[52:53], v[52:53], v[72:73], v[56:57]
	global_store_dwordx4 v[96:97], v[52:55], off offset:512 sc1
	s_nop 1
	v_lshlrev_b32_e32 v52, 16, v104
	v_and_b32_e32 v53, 0xffff0000, v104
	v_lshlrev_b32_e32 v54, 16, v105
	v_and_b32_e32 v55, 0xffff0000, v105
	s_waitcnt vmcnt(11)
	v_pk_fma_f32 v[46:47], v[46:47], v[78:79], v[54:55]
	v_pk_fma_f32 v[44:45], v[44:45], v[76:77], v[52:53]
	global_store_dwordx4 v[96:97], v[44:47], off offset:576 sc1
	v_add_u32_e32 v52, 0xffff8030, v118
	s_waitcnt vmcnt(11)
	v_lshlrev_b32_e32 v44, 16, v108
	v_and_b32_e32 v45, 0xffff0000, v108
	v_lshlrev_b32_e32 v46, 16, v109
	v_and_b32_e32 v47, 0xffff0000, v109
	s_waitcnt vmcnt(10)
	v_pk_fma_f32 v[46:47], v[50:51], v[82:83], v[46:47]
	v_pk_fma_f32 v[44:45], v[48:49], v[80:81], v[44:45]
	global_store_dwordx4 v[106:107], v[44:47], off sc1
	v_or_b32_e32 v48, 48, v118
	v_cmp_gt_i32_e64 s[6:7], s51, v48
	s_waitcnt vmcnt(10)
	v_lshlrev_b32_e32 v44, 16, v110
	v_and_b32_e32 v45, 0xffff0000, v110
	v_lshlrev_b32_e32 v46, 16, v111
	v_and_b32_e32 v47, 0xffff0000, v111
	s_waitcnt vmcnt(9)
	v_pk_fma_f32 v[42:43], v[42:43], v[86:87], v[46:47]
	v_pk_fma_f32 v[40:41], v[40:41], v[84:85], v[44:45]
	global_store_dwordx4 v[106:107], v[40:43], off offset:64 sc1
	v_cndmask_b32_e64 v48, v52, v48, s[6:7]
	v_ashrrev_i32_e32 v49, 31, v48
	s_waitcnt vmcnt(9)
	v_lshlrev_b32_e32 v40, 16, v112
	v_and_b32_e32 v41, 0xffff0000, v112
	v_lshlrev_b32_e32 v42, 16, v113
	v_and_b32_e32 v43, 0xffff0000, v113
	s_waitcnt vmcnt(8)
	v_pk_fma_f32 v[38:39], v[38:39], v[90:91], v[42:43]
	v_pk_fma_f32 v[36:37], v[36:37], v[88:89], v[40:41]
	global_store_dwordx4 v[106:107], v[36:39], off offset:512 sc1
	v_lshlrev_b64 v[48:49], 10, v[48:49]
	v_cndmask_b32_e64 v51, v154, v155, s[6:7]
	s_waitcnt vmcnt(8)
	v_lshlrev_b32_e32 v36, 16, v114
	v_and_b32_e32 v37, 0xffff0000, v114
	v_lshlrev_b32_e32 v38, 16, v115
	v_and_b32_e32 v39, 0xffff0000, v115
	s_waitcnt vmcnt(7)
	v_pk_fma_f32 v[34:35], v[34:35], v[94:95], v[38:39]
	v_pk_fma_f32 v[32:33], v[32:33], v[92:93], v[36:37]
	global_store_dwordx4 v[106:107], v[32:35], off offset:576 sc1
	v_add_u32_e32 v36, 0xffff8020, v118
	v_cndmask_b32_e64 v50, v156, v157, s[6:7]
	v_or_b32_e32 v32, 32, v118
	v_cmp_gt_i32_e32 vcc, s51, v32
	v_lshl_add_u64 v[74:75], v[48:49], 0, v[142:143]
	v_lshl_add_u64 v[60:61], v[74:75], 1, v[50:51]
	v_cndmask_b32_e32 v32, v36, v32, vcc
	v_ashrrev_i32_e32 v33, 31, v32
	v_lshlrev_b64 v[32:33], 10, v[32:33]
	v_cndmask_b32_e32 v35, v154, v155, vcc
	v_cndmask_b32_e32 v34, v156, v157, vcc
	v_lshl_add_u64 v[64:65], v[32:33], 0, v[142:143]
	v_lshl_add_u64 v[40:41], v[64:65], 1, v[34:35]
	global_load_dwordx2 v[66:67], v[40:41], off
	v_lshrrev_b32_e32 v32, 3, v36
	v_add_u32_e32 v32, 16, v32
	v_cndmask_b32_e32 v32, v32, v119, vcc
	v_mad_i64_i32 v[44:45], s[0:1], v32, s38, v[144:145]
	global_load_dwordx4 v[32:35], v[44:45], off
	global_load_dwordx2 v[68:69], v[40:41], off offset:32
	global_load_dwordx4 v[36:39], v[44:45], off offset:64
	global_load_dwordx2 v[70:71], v[40:41], off offset:256
	global_load_dwordx2 v[72:73], v[40:41], off offset:288
	s_nop 0
	global_load_dwordx4 v[40:43], v[44:45], off offset:512
	s_nop 0
	global_load_dwordx4 v[44:47], v[44:45], off offset:576
	v_lshrrev_b32_e32 v48, 3, v52
	global_load_dwordx2 v[76:77], v[60:61], off
	v_add_u32_e32 v48, 16, v48
	v_cndmask_b32_e64 v48, v48, v119, s[6:7]
	v_mad_i64_i32 v[62:63], s[0:1], v48, s38, v[144:145]
	global_load_dwordx4 v[48:51], v[62:63], off
	global_load_dwordx2 v[78:79], v[60:61], off offset:32
	global_load_dwordx4 v[52:55], v[62:63], off offset:64
	global_load_dwordx2 v[80:81], v[60:61], off offset:256
	global_load_dwordx4 v[56:59], v[62:63], off offset:512
	global_load_dwordx2 v[82:83], v[60:61], off offset:288
	s_nop 0
	global_load_dwordx4 v[60:63], v[62:63], off offset:576
	v_cndmask_b32_e32 v85, v158, v159, vcc
	v_cndmask_b32_e32 v84, v160, v161, vcc
	v_lshl_add_u64 v[64:65], v[64:65], 2, v[84:85]
	v_cndmask_b32_e64 v85, v158, v159, s[6:7]
	v_cndmask_b32_e64 v84, v160, v161, s[6:7]
	v_lshl_add_u64 v[74:75], v[74:75], 2, v[84:85]
	s_andn2_b64 vcc, exec, s[4:5]
	s_mov_b64 s[4:5], -1
	s_waitcnt vmcnt(15)
	v_lshlrev_b32_e32 v84, 16, v66
	v_and_b32_e32 v85, 0xffff0000, v66
	v_lshlrev_b32_e32 v66, 16, v67
	v_and_b32_e32 v67, 0xffff0000, v67
	s_waitcnt vmcnt(14)
	v_pk_fma_f32 v[30:31], v[30:31], v[34:35], v[66:67]
	v_pk_fma_f32 v[28:29], v[28:29], v[32:33], v[84:85]
	global_store_dwordx4 v[64:65], v[28:31], off sc1
	s_waitcnt vmcnt(14)
	s_nop 0
	v_lshlrev_b32_e32 v28, 16, v68
	v_and_b32_e32 v29, 0xffff0000, v68
	v_lshlrev_b32_e32 v30, 16, v69
	v_and_b32_e32 v31, 0xffff0000, v69
	s_waitcnt vmcnt(13)
	v_pk_fma_f32 v[26:27], v[26:27], v[38:39], v[30:31]
	v_pk_fma_f32 v[24:25], v[24:25], v[36:37], v[28:29]
	global_store_dwordx4 v[64:65], v[24:27], off offset:64 sc1
	s_waitcnt vmcnt(13)
	s_nop 0
	v_lshlrev_b32_e32 v24, 16, v70
	v_and_b32_e32 v25, 0xffff0000, v70
	v_lshlrev_b32_e32 v26, 16, v71
	v_and_b32_e32 v27, 0xffff0000, v71
	s_waitcnt vmcnt(11)
	v_pk_fma_f32 v[22:23], v[22:23], v[42:43], v[26:27]
	v_pk_fma_f32 v[20:21], v[20:21], v[40:41], v[24:25]
	global_store_dwordx4 v[64:65], v[20:23], off offset:512 sc1
	s_nop 1
	v_lshlrev_b32_e32 v20, 16, v72
	v_and_b32_e32 v21, 0xffff0000, v72
	v_lshlrev_b32_e32 v22, 16, v73
	v_and_b32_e32 v23, 0xffff0000, v73
	s_waitcnt vmcnt(11)
	v_pk_fma_f32 v[14:15], v[14:15], v[46:47], v[22:23]
	v_pk_fma_f32 v[12:13], v[12:13], v[44:45], v[20:21]
	global_store_dwordx4 v[64:65], v[12:15], off offset:576 sc1
	s_waitcnt vmcnt(11)
	s_nop 0
	v_lshlrev_b32_e32 v12, 16, v76
	v_and_b32_e32 v13, 0xffff0000, v76
	v_lshlrev_b32_e32 v14, 16, v77
	v_and_b32_e32 v15, 0xffff0000, v77
	s_waitcnt vmcnt(10)
	v_pk_fma_f32 v[14:15], v[18:19], v[50:51], v[14:15]
	v_pk_fma_f32 v[12:13], v[16:17], v[48:49], v[12:13]
	global_store_dwordx4 v[74:75], v[12:15], off sc1
	s_waitcnt vmcnt(10)
	s_nop 0
	v_lshlrev_b32_e32 v12, 16, v78
	v_and_b32_e32 v13, 0xffff0000, v78
	v_lshlrev_b32_e32 v14, 16, v79
	v_and_b32_e32 v15, 0xffff0000, v79
	s_waitcnt vmcnt(9)
	v_pk_fma_f32 v[10:11], v[10:11], v[54:55], v[14:15]
	v_pk_fma_f32 v[8:9], v[8:9], v[52:53], v[12:13]
	global_store_dwordx4 v[74:75], v[8:11], off offset:64 sc1
	s_waitcnt vmcnt(9)
	s_nop 0
	v_lshlrev_b32_e32 v8, 16, v80
	v_and_b32_e32 v9, 0xffff0000, v80
	v_lshlrev_b32_e32 v10, 16, v81
	v_and_b32_e32 v11, 0xffff0000, v81
	s_waitcnt vmcnt(8)
	v_pk_fma_f32 v[6:7], v[6:7], v[58:59], v[10:11]
	v_pk_fma_f32 v[4:5], v[4:5], v[56:57], v[8:9]
	global_store_dwordx4 v[74:75], v[4:7], off offset:512 sc1
	s_waitcnt vmcnt(8)
	s_nop 0
	v_lshlrev_b32_e32 v4, 16, v82
	v_and_b32_e32 v5, 0xffff0000, v82
	v_lshlrev_b32_e32 v6, 16, v83
	v_and_b32_e32 v7, 0xffff0000, v83
	s_waitcnt vmcnt(7)
	v_pk_fma_f32 v[2:3], v[2:3], v[62:63], v[6:7]
	v_pk_fma_f32 v[0:1], v[0:1], v[60:61], v[4:5]
	global_store_dwordx4 v[74:75], v[0:3], off offset:576 sc1
	s_cbranch_vccnz .LBB0_2137
	s_andn2_b64 vcc, exec, s[10:11]
	s_cbranch_vccnz .LBB0_2136
	s_barrier
	s_branch .LBB0_2136
